# second rmsnorm row loop: last four butterfly steps of each row's sum of squares done with DPP moves, on top of v70
# baseline (speedup 1.0000x reference)
; DEV u32x4 pack8(const float (&f)[8]) { u32x4 w; w.x = cvt_pk_bf16(f[0], f[1]); w.y = cvt_pk_bf16(f[2], f[3]); w.z = cvt_pk_bf16(f[4], f[5]); w.w = cvt_pk_bf16(f[6], f[7]); return w; }
; DEV float wave_sum(float v) {
; #pragma unroll
;     for (int o = 32; o >= 1; o >>= 1) v += __shfl_xor(v, o);
;     return v;
; }
; template <int RB>
; DEV void rmsnorm_rows(const float* srcf, const bf16_t* srcb, const float* gamma, bf16_t* H, bf16_t* cpy, float* outn, int row0, int lane) {
;     ...
;     for (int hf = 0; hf < 2; ++hf) { g0[hf] = *(const f32x4*)(gamma + hf * 512 + lane * 8); g1[hf] = *(const f32x4*)(gamma + hf * 512 + lane * 8 + 4); }
; #pragma unroll
;     for (int r = 0; r < RB; ++r) {
;         float ss = 0.f;
; #pragma unroll
;         for (int j = 0; j < 16; ++j) ss += v[r][j] * v[r][j];
;         ss = wave_sum(ss);
;         const float rs = rsqrtf(ss * (1.f / 1024.f) + EPS_);
;         const int row = row0 + r;
; #pragma unroll
;         for (int hf = 0; hf < 2; ++hf) { const int c = hf * 512 + lane * 8;
;             float y[8], x8[8];
; #pragma unroll
;             for (int j = 0; j < 4; ++j) { y[j] = v[r][hf * 8 + j] * rs * g0[hf][j]; y[4 + j] = v[r][hf * 8 + 4 + j] * rs * g1[hf][j]; }
; #pragma unroll
;             for (int j = 0; j < 8; ++j) x8[j] = v[r][hf * 8 + j];
;             if (cpy) *(u32x4*)(cpy + (size_t)row * 1024 + c) = pack8(x8);
.LBB0_1260:
	global_load_dwordx4 v[74:77], v[88:89], off offset:16
	global_load_dwordx4 v[78:81], v[88:89], off
	global_load_dwordx4 v[58:61], v[88:89], off offset:2064
	global_load_dwordx4 v[62:65], v[88:89], off offset:2048
	s_waitcnt vmcnt(19)
	v_mul_f32_e32 v0, v66, v66
	v_fmac_f32_e32 v0, v67, v67
	v_fmac_f32_e32 v0, v68, v68
	v_fmac_f32_e32 v0, v69, v69
	s_waitcnt vmcnt(18)
	v_fmac_f32_e32 v0, v70, v70
	v_fmac_f32_e32 v0, v71, v71
	v_fmac_f32_e32 v0, v72, v72
	v_fmac_f32_e32 v0, v73, v73
	s_waitcnt vmcnt(17)
	v_fmac_f32_e32 v0, v54, v54
	v_fmac_f32_e32 v0, v55, v55
	v_fmac_f32_e32 v0, v56, v56
	v_fmac_f32_e32 v0, v57, v57
	s_waitcnt vmcnt(16)
	v_pk_mul_f32 v[102:103], v[50:51], v[50:51]
	s_andn2_b64 vcc, exec, s[44:45]
	v_add_f32_e32 v0, v102, v0
	v_add_f32_e32 v0, v103, v0
	v_pk_mul_f32 v[102:103], v[52:53], v[52:53]
	s_nop 0
	v_add_f32_e32 v0, v102, v0
	v_add_f32_e32 v0, v103, v0
	ds_bpermute_b32 v93, v104, v0
	v_lshl_add_u64 v[102:103], s[38:39], 0, v[100:101]
	s_waitcnt lgkmcnt(0)
	v_add_f32_e32 v0, v0, v93
	ds_bpermute_b32 v93, v105, v0
	s_waitcnt lgkmcnt(0)
	v_add_f32_e32 v0, v0, v93
	s_nop 1
	v_mov_b32_dpp v93, v0 row_mirror row_mask:0xf bank_mask:0xf
	s_waitcnt lgkmcnt(0)
	v_add_f32_e32 v0, v0, v93
	s_nop 1
	v_mov_b32_dpp v93, v0 row_half_mirror row_mask:0xf bank_mask:0xf
	s_waitcnt lgkmcnt(0)
	v_add_f32_e32 v0, v0, v93
	s_nop 1
	v_mov_b32_dpp v93, v0 quad_perm:[2,3,0,1] row_mask:0xf bank_mask:0xf
	s_waitcnt lgkmcnt(0)
	v_add_f32_e32 v93, v0, v93
	s_nop 1
	v_mov_b32_dpp v95, v93 quad_perm:[1,0,3,2] row_mask:0xf bank_mask:0xf
	v_cndmask_b32_e64 v0, 0, 1, s[44:45]
	v_cmp_ne_u32_e64 s[40:41], 1, v0
	v_lshlrev_b32_e32 v0, 1, v82
	s_cbranch_vccnz .LBB0_1262
	v_lshl_add_u64 v[114:115], v[102:103], 0, v[0:1]
	v_cvt_pk_bf16_f32 v110, v66, v67
	v_cvt_pk_bf16_f32 v111, v68, v69
	v_cvt_pk_bf16_f32 v112, v70, v71
	v_cvt_pk_bf16_f32 v113, v72, v73
	global_store_dwordx4 v[114:115], v[110:113], off

; DEV u32x4 pack8(const float (&f)[8]) { u32x4 w; w.x = cvt_pk_bf16(f[0], f[1]); w.y = cvt_pk_bf16(f[2], f[3]); w.z = cvt_pk_bf16(f[4], f[5]); w.w = cvt_pk_bf16(f[6], f[7]); return w; }
; DEV float wave_sum(float v) {
; #pragma unroll
;     for (int o = 32; o >= 1; o >>= 1) v += __shfl_xor(v, o);
;     return v;
; }
; template <int RB>
; DEV void rmsnorm_rows(const float* srcf, const bf16_t* srcb, const float* gamma, bf16_t* H, bf16_t* cpy, float* outn, int row0, int lane) {
;     ...
;     for (int r = 0; r < RB; ++r) {
;         float ss = 0.f;
; #pragma unroll
;         for (int j = 0; j < 16; ++j) ss += v[r][j] * v[r][j];
;         ss = wave_sum(ss);
;         const float rs = rsqrtf(ss * (1.f / 1024.f) + EPS_);
;         const int row = row0 + r;
; #pragma unroll
;         for (int hf = 0; hf < 2; ++hf) { const int c = hf * 512 + lane * 8;
;             float y[8], x8[8];
; #pragma unroll
;             for (int j = 0; j < 4; ++j) { y[j] = v[r][hf * 8 + j] * rs * g0[hf][j]; y[4 + j] = v[r][hf * 8 + 4 + j] * rs * g1[hf][j]; }
; #pragma unroll
;             for (int j = 0; j < 8; ++j) x8[j] = v[r][hf * 8 + j];
;             if (cpy) *(u32x4*)(cpy + (size_t)row * 1024 + c) = pack8(x8);
;             if (outn) { *(f32x4*)(outn + (size_t)row * 1024 + c) = (f32x4){y[0], y[1], y[2], y[3]}; *(f32x4*)(outn + (size_t)row * 1024 + c + 4) = (f32x4){y[4], y[5], y[6], y[7]}; }
;             if (H) *(u32x4*)(H + (size_t)row * 1024 + c) = pack8(y); }
.LBB0_1264:
	s_nop 1
	v_mul_f32_e32 v70, v42, v42
	v_fmac_f32_e32 v70, v43, v43
	v_fmac_f32_e32 v70, v44, v44
	v_fmac_f32_e32 v70, v45, v45
	v_fmac_f32_e32 v70, v46, v46
	v_fmac_f32_e32 v70, v47, v47
	v_fmac_f32_e32 v70, v48, v48
	v_fmac_f32_e32 v70, v49, v49
	v_fmac_f32_e32 v70, v38, v38
	v_fmac_f32_e32 v70, v39, v39
	v_fmac_f32_e32 v70, v40, v40
	v_fmac_f32_e32 v70, v41, v41
	v_pk_mul_f32 v[68:69], v[30:31], v[30:31]
	v_mul_f32_e32 v50, v50, v93
	v_add_f32_e32 v68, v68, v70
	v_add_f32_e32 v70, v69, v68
	v_pk_mul_f32 v[68:69], v[32:33], v[32:33]
	v_mul_f32_e32 v51, v51, v93
	v_add_f32_e32 v68, v68, v70
	v_add_f32_e32 v68, v69, v68
	ds_bpermute_b32 v69, v104, v68
	s_waitcnt vmcnt(2)
	v_mul_f32_e32 v70, v58, v50
	v_mul_f32_e32 v50, v55, v93
	v_mul_f32_e32 v54, v54, v93
	s_waitcnt vmcnt(1)
	v_mul_f32_e32 v54, v62, v54
	s_waitcnt lgkmcnt(0)
	v_add_f32_e32 v55, v68, v69
	ds_bpermute_b32 v68, v105, v55
	v_mul_f32_e32 v69, v59, v51
	v_mul_f32_e32 v51, v56, v93
	v_mul_f32_e32 v50, v63, v50
	v_cvt_pk_bf16_f32 v50, v54, v50
	s_waitcnt lgkmcnt(0)
	v_add_f32_e32 v55, v55, v68
	s_nop 1
	v_mov_b32_dpp v56, v55 row_mirror row_mask:0xf bank_mask:0xf
	v_mul_f32_e32 v52, v52, v93
	v_mul_f32_e32 v68, v60, v52
	v_mul_f32_e32 v52, v57, v93
	v_mul_f32_e32 v53, v53, v93
	s_waitcnt lgkmcnt(0)
	v_add_f32_e32 v55, v55, v56
	s_nop 1
	v_mov_b32_dpp v56, v55 row_half_mirror row_mask:0xf bank_mask:0xf
	v_mul_f32_e32 v51, v64, v51
	v_mul_f32_e32 v52, v65, v52
	v_mul_f32_e32 v53, v61, v53
	v_cvt_pk_bf16_f32 v51, v51, v52
	s_waitcnt lgkmcnt(0)
	v_add_f32_e32 v54, v55, v56
	s_nop 1
	v_mov_b32_dpp v55, v54 quad_perm:[2,3,0,1] row_mask:0xf bank_mask:0xf
	v_cvt_pk_bf16_f32 v52, v70, v69
	v_cvt_pk_bf16_f32 v53, v68, v53
	v_ashrrev_i32_e32 v99, 31, v98
	global_store_dwordx4 v[66:67], v[50:53], off offset:1024
	s_waitcnt lgkmcnt(0)
	v_add_f32_e32 v54, v54, v55
	s_nop 1
	v_mov_b32_dpp v55, v54 quad_perm:[1,0,3,2] row_mask:0xf bank_mask:0xf
	v_lshlrev_b64 v[52:53], 11, v[98:99]
	s_and_b64 vcc, exec, s[40:41]
	v_lshl_add_u64 v[50:51], s[38:39], 0, v[52:53]
	s_cbranch_vccnz .LBB0_1266
	v_lshl_add_u64 v[56:57], v[50:51], 0, v[0:1]
	v_cvt_pk_bf16_f32 v66, v42, v43
	v_cvt_pk_bf16_f32 v67, v44, v45
	v_cvt_pk_bf16_f32 v68, v46, v47
	v_cvt_pk_bf16_f32 v69, v48, v49
	global_store_dwordx4 v[56:57], v[66:69], off

; DEV u32x4 pack8(const float (&f)[8]) { u32x4 w; w.x = cvt_pk_bf16(f[0], f[1]); w.y = cvt_pk_bf16(f[2], f[3]); w.z = cvt_pk_bf16(f[4], f[5]); w.w = cvt_pk_bf16(f[6], f[7]); return w; }
; DEV float wave_sum(float v) {
; #pragma unroll
;     for (int o = 32; o >= 1; o >>= 1) v += __shfl_xor(v, o);
;     return v;
; }
; template <int RB>
; DEV void rmsnorm_rows(const float* srcf, const bf16_t* srcb, const float* gamma, bf16_t* H, bf16_t* cpy, float* outn, int row0, int lane) {
;     ...
;     for (int r = 0; r < RB; ++r) {
;         float ss = 0.f;
; #pragma unroll
;         for (int j = 0; j < 16; ++j) ss += v[r][j] * v[r][j];
;         ss = wave_sum(ss);
;         const float rs = rsqrtf(ss * (1.f / 1024.f) + EPS_);
;         const int row = row0 + r;
; #pragma unroll
;         for (int hf = 0; hf < 2; ++hf) { const int c = hf * 512 + lane * 8;
;             float y[8], x8[8];
; #pragma unroll
;             for (int j = 0; j < 4; ++j) { y[j] = v[r][hf * 8 + j] * rs * g0[hf][j]; y[4 + j] = v[r][hf * 8 + 4 + j] * rs * g1[hf][j]; }
; #pragma unroll
;             for (int j = 0; j < 8; ++j) x8[j] = v[r][hf * 8 + j];
;             if (cpy) *(u32x4*)(cpy + (size_t)row * 1024 + c) = pack8(x8);
;             if (outn) { *(f32x4*)(outn + (size_t)row * 1024 + c) = (f32x4){y[0], y[1], y[2], y[3]}; *(f32x4*)(outn + (size_t)row * 1024 + c + 4) = (f32x4){y[4], y[5], y[6], y[7]}; }
;             if (H) *(u32x4*)(H + (size_t)row * 1024 + c) = pack8(y); }
.LBB0_1268:
	s_nop 1
	v_mul_f32_e32 v46, v26, v26
	v_fmac_f32_e32 v46, v27, v27
	v_fmac_f32_e32 v46, v28, v28
	v_fmac_f32_e32 v46, v29, v29
	v_fmac_f32_e32 v46, v34, v34
	v_fmac_f32_e32 v46, v35, v35
	v_fmac_f32_e32 v46, v36, v36
	v_fmac_f32_e32 v46, v37, v37
	v_fmac_f32_e32 v46, v22, v22
	v_fmac_f32_e32 v46, v23, v23
	v_fmac_f32_e32 v46, v24, v24
	v_fmac_f32_e32 v46, v25, v25
	v_pk_mul_f32 v[44:45], v[14:15], v[14:15]
	v_mul_f32_e32 v30, v30, v54
	v_add_f32_e32 v44, v44, v46
	v_add_f32_e32 v46, v45, v44
	v_pk_mul_f32 v[44:45], v[16:17], v[16:17]
	v_mul_f32_e32 v31, v31, v54
	v_add_f32_e32 v44, v44, v46
	v_add_f32_e32 v44, v45, v44
	ds_bpermute_b32 v45, v104, v44
	v_mul_f32_e32 v46, v58, v30
	v_mul_f32_e32 v30, v39, v54
	v_mul_f32_e32 v38, v38, v54
	v_mul_f32_e32 v38, v62, v38
	s_waitcnt lgkmcnt(0)
	v_add_f32_e32 v39, v44, v45
	ds_bpermute_b32 v44, v105, v39
	v_mul_f32_e32 v45, v59, v31
	v_mul_f32_e32 v31, v40, v54
	v_mul_f32_e32 v30, v63, v30
	v_cvt_pk_bf16_f32 v30, v38, v30
	s_waitcnt lgkmcnt(0)
	v_add_f32_e32 v39, v39, v44
	s_nop 1
	v_mov_b32_dpp v40, v39 row_mirror row_mask:0xf bank_mask:0xf
	v_mul_f32_e32 v32, v32, v54
	v_mul_f32_e32 v44, v60, v32
	v_mul_f32_e32 v32, v41, v54
	v_mul_f32_e32 v33, v33, v54
	s_waitcnt lgkmcnt(0)
	v_add_f32_e32 v39, v39, v40
	s_nop 1
	v_mov_b32_dpp v40, v39 row_half_mirror row_mask:0xf bank_mask:0xf
	v_mul_f32_e32 v31, v64, v31
	v_mul_f32_e32 v32, v65, v32
	v_mul_f32_e32 v33, v61, v33
	v_cvt_pk_bf16_f32 v31, v31, v32
	s_waitcnt lgkmcnt(0)
	v_add_f32_e32 v38, v39, v40
	s_nop 1
	v_mov_b32_dpp v39, v38 quad_perm:[2,3,0,1] row_mask:0xf bank_mask:0xf
	v_cvt_pk_bf16_f32 v32, v46, v45
	v_cvt_pk_bf16_f32 v33, v44, v33
	v_ashrrev_i32_e32 v97, 31, v96
	global_store_dwordx4 v[42:43], v[30:33], off offset:1024
	s_waitcnt lgkmcnt(0)
	v_add_f32_e32 v38, v38, v39
	s_nop 1
	v_mov_b32_dpp v39, v38 quad_perm:[1,0,3,2] row_mask:0xf bank_mask:0xf
	v_lshlrev_b64 v[32:33], 11, v[96:97]
	s_and_b64 vcc, exec, s[40:41]
	v_lshl_add_u64 v[30:31], s[38:39], 0, v[32:33]
	s_cbranch_vccnz .LBB0_1270
	v_lshl_add_u64 v[44:45], v[30:31], 0, v[0:1]
	v_cvt_pk_bf16_f32 v40, v26, v27
	v_cvt_pk_bf16_f32 v41, v28, v29
	v_cvt_pk_bf16_f32 v42, v34, v35
	v_cvt_pk_bf16_f32 v43, v36, v37
	global_store_dwordx4 v[44:45], v[40:43], off

; DEV u32x4 pack8(const float (&f)[8]) { u32x4 w; w.x = cvt_pk_bf16(f[0], f[1]); w.y = cvt_pk_bf16(f[2], f[3]); w.z = cvt_pk_bf16(f[4], f[5]); w.w = cvt_pk_bf16(f[6], f[7]); return w; }
; DEV float wave_sum(float v) {
; #pragma unroll
;     for (int o = 32; o >= 1; o >>= 1) v += __shfl_xor(v, o);
;     return v;
; }
; template <int RB>
; DEV void rmsnorm_rows(const float* srcf, const bf16_t* srcb, const float* gamma, bf16_t* H, bf16_t* cpy, float* outn, int row0, int lane) {
;     ...
;     for (int r = 0; r < RB; ++r) {
;         float ss = 0.f;
; #pragma unroll
;         for (int j = 0; j < 16; ++j) ss += v[r][j] * v[r][j];
;         ss = wave_sum(ss);
;         const float rs = rsqrtf(ss * (1.f / 1024.f) + EPS_);
;         const int row = row0 + r;
; #pragma unroll
;         for (int hf = 0; hf < 2; ++hf) { const int c = hf * 512 + lane * 8;
;             float y[8], x8[8];
; #pragma unroll
;             for (int j = 0; j < 4; ++j) { y[j] = v[r][hf * 8 + j] * rs * g0[hf][j]; y[4 + j] = v[r][hf * 8 + 4 + j] * rs * g1[hf][j]; }
; #pragma unroll
;             for (int j = 0; j < 8; ++j) x8[j] = v[r][hf * 8 + j];
;             if (cpy) *(u32x4*)(cpy + (size_t)row * 1024 + c) = pack8(x8);
;             if (outn) { *(f32x4*)(outn + (size_t)row * 1024 + c) = (f32x4){y[0], y[1], y[2], y[3]}; *(f32x4*)(outn + (size_t)row * 1024 + c + 4) = (f32x4){y[4], y[5], y[6], y[7]}; }
;             if (H) *(u32x4*)(H + (size_t)row * 1024 + c) = pack8(y); }
.LBB0_1272:
	v_mul_f32_e32 v30, v18, v18
	v_fmac_f32_e32 v30, v19, v19
	v_fmac_f32_e32 v30, v20, v20
	v_fmac_f32_e32 v30, v21, v21
	v_fmac_f32_e32 v30, v10, v10
	v_fmac_f32_e32 v30, v11, v11
	v_fmac_f32_e32 v30, v12, v12
	v_fmac_f32_e32 v30, v13, v13
	v_fmac_f32_e32 v30, v2, v2
	v_fmac_f32_e32 v30, v3, v3
	v_fmac_f32_e32 v30, v4, v4
	v_fmac_f32_e32 v30, v5, v5
	v_pk_mul_f32 v[28:29], v[6:7], v[6:7]
	v_mul_f32_e32 v14, v14, v38
	v_add_f32_e32 v28, v30, v28
	v_add_f32_e32 v30, v28, v29
	v_pk_mul_f32 v[28:29], v[8:9], v[8:9]
	v_mul_f32_e32 v15, v15, v38
	v_add_f32_e32 v28, v30, v28
	v_add_f32_e32 v28, v28, v29
	ds_bpermute_b32 v29, v104, v28
	v_mul_f32_e32 v30, v58, v14
	v_mul_f32_e32 v14, v23, v38
	v_mul_f32_e32 v22, v22, v38
	v_mul_f32_e32 v22, v62, v22
	s_waitcnt lgkmcnt(0)
	v_add_f32_e32 v23, v28, v29
	ds_bpermute_b32 v28, v105, v23
	v_mul_f32_e32 v29, v59, v15
	v_mul_f32_e32 v15, v24, v38
	v_mul_f32_e32 v14, v63, v14
	v_cvt_pk_bf16_f32 v14, v22, v14
	s_waitcnt lgkmcnt(0)
	v_add_f32_e32 v23, v23, v28
	s_nop 1
	v_mov_b32_dpp v24, v23 row_mirror row_mask:0xf bank_mask:0xf
	v_mul_f32_e32 v16, v16, v38
	v_mul_f32_e32 v28, v60, v16
	v_mul_f32_e32 v16, v25, v38
	v_mul_f32_e32 v17, v17, v38
	s_waitcnt lgkmcnt(0)
	v_add_f32_e32 v23, v23, v24
	s_nop 1
	v_mov_b32_dpp v24, v23 row_half_mirror row_mask:0xf bank_mask:0xf
	v_mul_f32_e32 v15, v64, v15
	v_mul_f32_e32 v16, v65, v16
	v_mul_f32_e32 v17, v61, v17
	v_cvt_pk_bf16_f32 v15, v15, v16
	s_waitcnt lgkmcnt(0)
	v_add_f32_e32 v22, v23, v24
	s_nop 1
	v_mov_b32_dpp v23, v22 quad_perm:[2,3,0,1] row_mask:0xf bank_mask:0xf
	v_cvt_pk_bf16_f32 v16, v30, v29
	v_cvt_pk_bf16_f32 v17, v28, v17
	v_ashrrev_i32_e32 v95, 31, v94
	global_store_dwordx4 v[26:27], v[14:17], off offset:1024
	s_waitcnt lgkmcnt(0)
	v_add_f32_e32 v22, v22, v23
	s_nop 1
	v_mov_b32_dpp v23, v22 quad_perm:[1,0,3,2] row_mask:0xf bank_mask:0xf
	v_lshlrev_b64 v[16:17], 11, v[94:95]
	s_and_b64 vcc, exec, s[40:41]
	v_lshl_add_u64 v[14:15], s[38:39], 0, v[16:17]
	s_cbranch_vccnz .LBB0_1274
	v_lshl_add_u64 v[28:29], v[14:15], 0, v[0:1]
	v_cvt_pk_bf16_f32 v24, v18, v19
	v_cvt_pk_bf16_f32 v25, v20, v21
	v_cvt_pk_bf16_f32 v26, v10, v11
	v_cvt_pk_bf16_f32 v27, v12, v13
	global_store_dwordx4 v[28:29], v[24:27], off
